# K-split third round with two half-tile owners; deferred weight transposes split between the idle tails of down GEMM 1 and w_out GEMM
# speedup vs baseline: 1.0390x; 1.0103x over previous
; template <class Epi, class Sched, bool ALIGN_EPI = false, bool SP2 = false>
; __device__ __forceinline__ void gemm_phase(PG8_LAS unsigned char* lds, const Gemm g, const Sched& S, const Epi& E) {
;     ...
;         const bool has_next = S.next(ui + 1, nxt);
;         const char* nA = has_next ? (const char*)g.A + (size_t)nxt.pm * tstep + (size_t)nxt.kt0 * kstepA : cA; const char* nB = has_next ? (const char*)g.Bt + (size_t)nxt.pn * tstep + (size_t)nxt.kt0 * kstep : cB;
;         const int nt = cur.nkt;
.LBB0_441:
	s_andn2_b64 vcc, exec, s[4:5]
	s_mov_b32 s43, s69
	s_mov_b32 s42, s78
	s_mov_b64 s[20:21], s[16:17]
	s_mov_b64 s[18:19], s[14:15]
	s_mov_b32 s101, s100
	s_cmp_eq_u32 s100, 0
	s_cbranch_scc1 .Lsk_cur_done
	s_and_b32 s2, s100, 2
	s_cmp_eq_u32 s2, 0
	s_cselect_b32 s39, 12, 10

; template <class Epi, class Sched, bool ALIGN_EPI = false, bool SP2 = false>
; __device__ __forceinline__ void gemm_phase(PG8_LAS unsigned char* lds, const Gemm g, const Sched& S, const Epi& E) {
;     ...
;         const bool has_next = S.next(ui + 1, nxt);
;         const char* nA = has_next ? (const char*)g.A + (size_t)nxt.pm * tstep + (size_t)nxt.kt0 * kstepA : cA; const char* nB = has_next ? (const char*)g.Bt + (size_t)nxt.pn * tstep + (size_t)nxt.kt0 * kstep : cB;
.LBB0_448:
	s_cmp_eq_u32 s100, 0
	s_cbranch_scc1 .Lsk_ptr_done
	s_and_b32 s2, s100, 3
	s_mul_i32 s22, s2, 12
	s_cmp_eq_u32 s2, 3
	s_cselect_b32 s22, 34, s22
	s_lshl_b32 s23, s22, 15
	s_add_u32 s14, s14, s23
	s_addc_u32 s15, s15, 0
	s_lshl_b32 s23, s22, 7
	s_add_u32 s16, s16, s23
	s_addc_u32 s17, s17, 0

; #define PG8_BAR __builtin_amdgcn_s_barrier()
; template <class Epi, class Sched, bool ALIGN_EPI = false, bool SP2 = false>
; __device__ __forceinline__ void gemm_phase(PG8_LAS unsigned char* lds, const Gemm g, const Sched& S, const Epi& E) {
;     ...
;         if constexpr (ALIGN_EPI) { if (wr == 0) PG8_BAR; }
;         if constexpr (!Epi::AFTER_DRAIN) { E(acc, cur, wr, wc, fr, fq); S.done(cur); }
;         if (!has_next) break;
.LBB0_452:
	s_cmp_eq_u32 s101, 0
	s_cbranch_scc1 .Lsk_epi_normal
	v_readlane_b32 s6, v255, 49
	v_readlane_b32 s84, v255, 37
	v_readlane_b32 s85, v255, 38
	v_readlane_b32 s86, v255, 29
	v_readlane_b32 s87, v255, 30
	s_bfe_u32 s7, s101, 0x50008
	s_and_b32 s22, s101, 3
	v_and_b32_e32 v186, 63, v194
	v_lshlrev_b32_e32 v186, 4, v186
	s_lshl_b32 s23, s7, 8
	s_movk_i32 s2, 0x4000
	s_cmp_eq_u32 s77, 3
	s_cselect_b32 s2, 0x2000, s2
	s_add_i32 s23, s23, s2
	s_add_u32 s86, s86, s23
	s_addc_u32 s87, s87, 0
	s_lshl_b32 s6, s6, 15
	s_lshl_b32 s23, s7, 20
	s_add_i32 s23, s23, s6
	s_add_u32 s82, s84, s23
	s_addc_u32 s83, s85, 0
	s_lshl_b32 s23, s22, 18
	s_add_u32 s84, s82, s23
	s_addc_u32 s85, s83, 0
	s_cmp_eq_u32 s22, 2
	s_cbranch_scc1 .Lsk_st_lo
	s_cmp_eq_u32 s22, 3
	s_cbranch_scc1 .Lsk_st_hi
	global_store_dwordx4 v186, v[0:3], s[84:85]
	global_store_dwordx4 v186, v[4:7], s[84:85] offset:1024
	global_store_dwordx4 v186, v[8:11], s[84:85] offset:2048
	global_store_dwordx4 v186, v[12:15], s[84:85] offset:3072
	s_add_u32 s84, s84, 0x1000
	s_addc_u32 s85, s85, 0
	global_store_dwordx4 v186, v[16:19], s[84:85]
	global_store_dwordx4 v186, v[20:23], s[84:85] offset:1024
	global_store_dwordx4 v186, v[24:27], s[84:85] offset:2048
	global_store_dwordx4 v186, v[28:31], s[84:85] offset:3072
	s_add_u32 s84, s84, 0x1000
	s_addc_u32 s85, s85, 0
	global_store_dwordx4 v186, v[32:35], s[84:85]
	global_store_dwordx4 v186, v[36:39], s[84:85] offset:1024
	global_store_dwordx4 v186, v[40:43], s[84:85] offset:2048
	global_store_dwordx4 v186, v[44:47], s[84:85] offset:3072
	s_add_u32 s84, s84, 0x1000
	s_addc_u32 s85, s85, 0
	global_store_dwordx4 v186, v[48:51], s[84:85]
	global_store_dwordx4 v186, v[52:55], s[84:85] offset:1024
	global_store_dwordx4 v186, v[56:59], s[84:85] offset:2048
	global_store_dwordx4 v186, v[60:63], s[84:85] offset:3072
	s_add_u32 s84, s84, 0x1000
	s_addc_u32 s85, s85, 0
	global_store_dwordx4 v186, v[64:67], s[84:85]
	global_store_dwordx4 v186, v[68:71], s[84:85] offset:1024
	global_store_dwordx4 v186, v[72:75], s[84:85] offset:2048
	global_store_dwordx4 v186, v[76:79], s[84:85] offset:3072
	s_add_u32 s84, s84, 0x1000
	s_addc_u32 s85, s85, 0
	global_store_dwordx4 v186, v[80:83], s[84:85]
	global_store_dwordx4 v186, v[84:87], s[84:85] offset:1024
	global_store_dwordx4 v186, v[88:91], s[84:85] offset:2048
	global_store_dwordx4 v186, v[92:95], s[84:85] offset:3072
	s_add_u32 s84, s84, 0x1000
	s_addc_u32 s85, s85, 0
	global_store_dwordx4 v186, v[96:99], s[84:85]
	global_store_dwordx4 v186, v[100:103], s[84:85] offset:1024
	global_store_dwordx4 v186, v[104:107], s[84:85] offset:2048
	global_store_dwordx4 v186, v[108:111], s[84:85] offset:3072
	s_add_u32 s84, s84, 0x1000
	s_addc_u32 s85, s85, 0
	global_store_dwordx4 v186, v[112:115], s[84:85]
	global_store_dwordx4 v186, v[116:119], s[84:85] offset:1024
	global_store_dwordx4 v186, v[120:123], s[84:85] offset:2048
	global_store_dwordx4 v186, v[124:127], s[84:85] offset:3072
	s_branch .Lsk_publish
.Lsk_st_lo:
	global_store_dwordx4 v186, v[0:3], s[84:85]
	global_store_dwordx4 v186, v[4:7], s[84:85] offset:1024
	global_store_dwordx4 v186, v[8:11], s[84:85] offset:2048
	global_store_dwordx4 v186, v[12:15], s[84:85] offset:3072
	s_add_u32 s84, s84, 0x1000
	s_addc_u32 s85, s85, 0
	global_store_dwordx4 v186, v[16:19], s[84:85]
	global_store_dwordx4 v186, v[20:23], s[84:85] offset:1024
	global_store_dwordx4 v186, v[24:27], s[84:85] offset:2048
	global_store_dwordx4 v186, v[28:31], s[84:85] offset:3072
	s_add_u32 s84, s84, 0x1000
	s_addc_u32 s85, s85, 0
	global_store_dwordx4 v186, v[32:35], s[84:85]
	global_store_dwordx4 v186, v[36:39], s[84:85] offset:1024
	global_store_dwordx4 v186, v[40:43], s[84:85] offset:2048
	global_store_dwordx4 v186, v[44:47], s[84:85] offset:3072
	s_add_u32 s84, s84, 0x1000
	s_addc_u32 s85, s85, 0
	global_store_dwordx4 v186, v[48:51], s[84:85]
	global_store_dwordx4 v186, v[52:55], s[84:85] offset:1024
	global_store_dwordx4 v186, v[56:59], s[84:85] offset:2048
	global_store_dwordx4 v186, v[60:63], s[84:85] offset:3072
	s_branch .Lsk_publish
.Lsk_st_hi:
	s_add_u32 s84, s84, 0x4000
	s_addc_u32 s85, s85, 0
	global_store_dwordx4 v186, v[64:67], s[84:85]
	global_store_dwordx4 v186, v[68:71], s[84:85] offset:1024
	global_store_dwordx4 v186, v[72:75], s[84:85] offset:2048
	global_store_dwordx4 v186, v[76:79], s[84:85] offset:3072
	s_add_u32 s84, s84, 0x1000
	s_addc_u32 s85, s85, 0
	global_store_dwordx4 v186, v[80:83], s[84:85]
	global_store_dwordx4 v186, v[84:87], s[84:85] offset:1024
	global_store_dwordx4 v186, v[88:91], s[84:85] offset:2048
	global_store_dwordx4 v186, v[92:95], s[84:85] offset:3072
	s_add_u32 s84, s84, 0x1000
	s_addc_u32 s85, s85, 0
	global_store_dwordx4 v186, v[96:99], s[84:85]
	global_store_dwordx4 v186, v[100:103], s[84:85] offset:1024
	global_store_dwordx4 v186, v[104:107], s[84:85] offset:2048
	global_store_dwordx4 v186, v[108:111], s[84:85] offset:3072
	s_add_u32 s84, s84, 0x1000
	s_addc_u32 s85, s85, 0
	global_store_dwordx4 v186, v[112:115], s[84:85]
	global_store_dwordx4 v186, v[116:119], s[84:85] offset:1024
	global_store_dwordx4 v186, v[120:123], s[84:85] offset:2048
	global_store_dwordx4 v186, v[124:127], s[84:85] offset:3072
.Lsk_publish:
	s_waitcnt vmcnt(0)
	s_barrier
	s_cmp_lg_u32 s6, 0
	s_cbranch_scc1 .Lsk_pub_done
	buffer_wbl2 sc1
	s_waitcnt vmcnt(0)
	s_mov_b64 s[84:85], exec
	s_mov_b64 exec, 1
	global_atomic_add v161, v196, s[86:87]
	s_mov_b64 exec, s[84:85]
	s_waitcnt vmcnt(0)
.Lsk_pub_done:
	s_cmp_lt_u32 s22, 2
	s_cbranch_scc0 .Lsk_owner
	s_mov_b64 s[4:5], -1
	s_branch .LBB0_441
.Lsk_owner:
	s_mov_b32 s23, 0
; template <class Epi, class Sched, bool ALIGN_EPI = false, bool SP2 = false>
; __device__ __forceinline__ void gemm_phase(PG8_LAS unsigned char* lds, const Gemm g, const Sched& S, const Epi& E) {
;     ...
;         if constexpr (!Epi::AFTER_DRAIN) { E(acc, cur, wr, wc, fr, fq); S.done(cur); }
.Lsk_poll:
	global_load_dword v187, v161, s[86:87] sc1
	s_waitcnt vmcnt(0)
	v_readfirstlane_b32 s2, v187
	s_add_i32 s23, s23, 1
	s_cmp_ge_u32 s2, 4
	s_cbranch_scc1 .Lsk_ready
	s_cmp_gt_u32 s23, 0x40000
	s_cbranch_scc1 .Lsk_ready
	s_sleep 2
	s_branch .Lsk_poll
.Lsk_ready:
	buffer_inv sc1
	s_waitcnt vmcnt(0)
	s_cmp_eq_u32 s22, 3
	s_cbranch_scc1 .Lsk_rd_hi
	s_add_u32 s84, s82, 0x4000
	s_addc_u32 s85, s83, 0
	global_load_dwordx4 v[128:131], v186, s[84:85]
	global_load_dwordx4 v[132:135], v186, s[84:85] offset:1024
	global_load_dwordx4 v[136:139], v186, s[84:85] offset:2048
	global_load_dwordx4 v[140:143], v186, s[84:85] offset:3072
	s_add_u32 s84, s84, 0x1000
	s_addc_u32 s85, s85, 0
	global_load_dwordx4 v[144:147], v186, s[84:85]
	global_load_dwordx4 v[148:151], v186, s[84:85] offset:1024
	global_load_dwordx4 v[152:155], v186, s[84:85] offset:2048
	global_load_dwordx4 v[156:159], v186, s[84:85] offset:3072
	s_add_u32 s84, s84, 0x1000
	s_addc_u32 s85, s85, 0
	global_load_dwordx4 v[212:215], v186, s[84:85]
	global_load_dwordx4 v[216:219], v186, s[84:85] offset:1024
	global_load_dwordx4 v[220:223], v186, s[84:85] offset:2048
	global_load_dwordx4 v[224:227], v186, s[84:85] offset:3072
	s_add_u32 s84, s84, 0x1000
	s_addc_u32 s85, s85, 0
	global_load_dwordx4 v[228:231], v186, s[84:85]
	global_load_dwordx4 v[232:235], v186, s[84:85] offset:1024
	global_load_dwordx4 v[188:191], v186, s[84:85] offset:2048
	global_load_dwordx4 v[236:239], v186, s[84:85] offset:3072
	s_waitcnt vmcnt(15)
	v_pk_add_f32 v[64:65], v[64:65], v[128:129]
	v_pk_add_f32 v[66:67], v[66:67], v[130:131]
	s_add_u32 s84, s84, 0x3d000
	s_addc_u32 s85, s85, 0
	global_load_dwordx4 v[128:131], v186, s[84:85]
	s_waitcnt vmcnt(15)
	v_pk_add_f32 v[68:69], v[68:69], v[132:133]
	v_pk_add_f32 v[70:71], v[70:71], v[134:135]
	global_load_dwordx4 v[132:135], v186, s[84:85] offset:1024
	s_waitcnt vmcnt(15)
	v_pk_add_f32 v[72:73], v[72:73], v[136:137]
	v_pk_add_f32 v[74:75], v[74:75], v[138:139]
	global_load_dwordx4 v[136:139], v186, s[84:85] offset:2048
	s_waitcnt vmcnt(15)
	v_pk_add_f32 v[76:77], v[76:77], v[140:141]
	v_pk_add_f32 v[78:79], v[78:79], v[142:143]
	global_load_dwordx4 v[140:143], v186, s[84:85] offset:3072
	s_waitcnt vmcnt(15)
	v_pk_add_f32 v[80:81], v[80:81], v[144:145]
	v_pk_add_f32 v[82:83], v[82:83], v[146:147]
	s_add_u32 s84, s84, 0x1000
	s_addc_u32 s85, s85, 0
	global_load_dwordx4 v[144:147], v186, s[84:85]
	s_waitcnt vmcnt(15)
	v_pk_add_f32 v[84:85], v[84:85], v[148:149]
	v_pk_add_f32 v[86:87], v[86:87], v[150:151]
	global_load_dwordx4 v[148:151], v186, s[84:85] offset:1024
	s_waitcnt vmcnt(15)
	v_pk_add_f32 v[88:89], v[88:89], v[152:153]
	v_pk_add_f32 v[90:91], v[90:91], v[154:155]
	global_load_dwordx4 v[152:155], v186, s[84:85] offset:2048
	s_waitcnt vmcnt(15)
	v_pk_add_f32 v[92:93], v[92:93], v[156:157]
	v_pk_add_f32 v[94:95], v[94:95], v[158:159]
	global_load_dwordx4 v[156:159], v186, s[84:85] offset:3072
	s_waitcnt vmcnt(15)
	v_pk_add_f32 v[96:97], v[96:97], v[212:213]
	v_pk_add_f32 v[98:99], v[98:99], v[214:215]
	s_add_u32 s84, s84, 0x1000
	s_addc_u32 s85, s85, 0
	global_load_dwordx4 v[212:215], v186, s[84:85]
	s_waitcnt vmcnt(15)
	v_pk_add_f32 v[100:101], v[100:101], v[216:217]
	v_pk_add_f32 v[102:103], v[102:103], v[218:219]
	global_load_dwordx4 v[216:219], v186, s[84:85] offset:1024
	s_waitcnt vmcnt(15)
	v_pk_add_f32 v[104:105], v[104:105], v[220:221]
	v_pk_add_f32 v[106:107], v[106:107], v[222:223]
	global_load_dwordx4 v[220:223], v186, s[84:85] offset:2048
	s_waitcnt vmcnt(15)
	v_pk_add_f32 v[108:109], v[108:109], v[224:225]
	v_pk_add_f32 v[110:111], v[110:111], v[226:227]
	global_load_dwordx4 v[224:227], v186, s[84:85] offset:3072
	s_waitcnt vmcnt(15)
	v_pk_add_f32 v[112:113], v[112:113], v[228:229]
	v_pk_add_f32 v[114:115], v[114:115], v[230:231]
	s_add_u32 s84, s84, 0x1000
	s_addc_u32 s85, s85, 0
	global_load_dwordx4 v[228:231], v186, s[84:85]
	s_waitcnt vmcnt(15)
	v_pk_add_f32 v[116:117], v[116:117], v[232:233]
	v_pk_add_f32 v[118:119], v[118:119], v[234:235]
	global_load_dwordx4 v[232:235], v186, s[84:85] offset:1024
	s_waitcnt vmcnt(15)
	v_pk_add_f32 v[120:121], v[120:121], v[188:189]
	v_pk_add_f32 v[122:123], v[122:123], v[190:191]
	global_load_dwordx4 v[188:191], v186, s[84:85] offset:2048
	s_waitcnt vmcnt(15)
	v_pk_add_f32 v[124:125], v[124:125], v[236:237]
	v_pk_add_f32 v[126:127], v[126:127], v[238:239]
	global_load_dwordx4 v[236:239], v186, s[84:85] offset:3072
	s_waitcnt vmcnt(15)
	v_pk_add_f32 v[64:65], v[64:65], v[128:129]
	v_pk_add_f32 v[66:67], v[66:67], v[130:131]
	s_add_u32 s84, s84, 0x7d000
	s_addc_u32 s85, s85, 0
	global_load_dwordx4 v[128:131], v186, s[84:85]
	s_waitcnt vmcnt(15)
	v_pk_add_f32 v[68:69], v[68:69], v[132:133]
	v_pk_add_f32 v[70:71], v[70:71], v[134:135]
	global_load_dwordx4 v[132:135], v186, s[84:85] offset:1024
	s_waitcnt vmcnt(15)
	v_pk_add_f32 v[72:73], v[72:73], v[136:137]
	v_pk_add_f32 v[74:75], v[74:75], v[138:139]
	global_load_dwordx4 v[136:139], v186, s[84:85] offset:2048
	s_waitcnt vmcnt(15)
	v_pk_add_f32 v[76:77], v[76:77], v[140:141]
	v_pk_add_f32 v[78:79], v[78:79], v[142:143]
	global_load_dwordx4 v[140:143], v186, s[84:85] offset:3072
	s_waitcnt vmcnt(15)
	v_pk_add_f32 v[80:81], v[80:81], v[144:145]
	v_pk_add_f32 v[82:83], v[82:83], v[146:147]
	s_add_u32 s84, s84, 0x1000
	s_addc_u32 s85, s85, 0
	global_load_dwordx4 v[144:147], v186, s[84:85]
	s_waitcnt vmcnt(15)
	v_pk_add_f32 v[84:85], v[84:85], v[148:149]
	v_pk_add_f32 v[86:87], v[86:87], v[150:151]
	global_load_dwordx4 v[148:151], v186, s[84:85] offset:1024
	s_waitcnt vmcnt(15)
; template <class Epi, class Sched, bool ALIGN_EPI = false, bool SP2 = false>
; __device__ __forceinline__ void gemm_phase(PG8_LAS unsigned char* lds, const Gemm g, const Sched& S, const Epi& E) {
;     ...
;         if constexpr (!Epi::AFTER_DRAIN) { E(acc, cur, wr, wc, fr, fq); S.done(cur); }
	v_pk_add_f32 v[88:89], v[88:89], v[152:153]
	v_pk_add_f32 v[90:91], v[90:91], v[154:155]
	global_load_dwordx4 v[152:155], v186, s[84:85] offset:2048
	s_waitcnt vmcnt(15)
	v_pk_add_f32 v[92:93], v[92:93], v[156:157]
	v_pk_add_f32 v[94:95], v[94:95], v[158:159]
	global_load_dwordx4 v[156:159], v186, s[84:85] offset:3072
	s_waitcnt vmcnt(15)
	v_pk_add_f32 v[96:97], v[96:97], v[212:213]
	v_pk_add_f32 v[98:99], v[98:99], v[214:215]
	s_add_u32 s84, s84, 0x1000
	s_addc_u32 s85, s85, 0
	global_load_dwordx4 v[212:215], v186, s[84:85]
	s_waitcnt vmcnt(15)
	v_pk_add_f32 v[100:101], v[100:101], v[216:217]
	v_pk_add_f32 v[102:103], v[102:103], v[218:219]
	global_load_dwordx4 v[216:219], v186, s[84:85] offset:1024
	s_waitcnt vmcnt(15)
	v_pk_add_f32 v[104:105], v[104:105], v[220:221]
	v_pk_add_f32 v[106:107], v[106:107], v[222:223]
	global_load_dwordx4 v[220:223], v186, s[84:85] offset:2048
	s_waitcnt vmcnt(15)
	v_pk_add_f32 v[108:109], v[108:109], v[224:225]
	v_pk_add_f32 v[110:111], v[110:111], v[226:227]
	global_load_dwordx4 v[224:227], v186, s[84:85] offset:3072
	s_waitcnt vmcnt(15)
	v_pk_add_f32 v[112:113], v[112:113], v[228:229]
	v_pk_add_f32 v[114:115], v[114:115], v[230:231]
	s_add_u32 s84, s84, 0x1000
	s_addc_u32 s85, s85, 0
	global_load_dwordx4 v[228:231], v186, s[84:85]
	s_waitcnt vmcnt(15)
	v_pk_add_f32 v[116:117], v[116:117], v[232:233]
	v_pk_add_f32 v[118:119], v[118:119], v[234:235]
	global_load_dwordx4 v[232:235], v186, s[84:85] offset:1024
	s_waitcnt vmcnt(15)
	v_pk_add_f32 v[120:121], v[120:121], v[188:189]
	v_pk_add_f32 v[122:123], v[122:123], v[190:191]
	global_load_dwordx4 v[188:191], v186, s[84:85] offset:2048
	s_waitcnt vmcnt(15)
	v_pk_add_f32 v[124:125], v[124:125], v[236:237]
	v_pk_add_f32 v[126:127], v[126:127], v[238:239]
	global_load_dwordx4 v[236:239], v186, s[84:85] offset:3072
	s_waitcnt vmcnt(15)
	v_pk_add_f32 v[64:65], v[64:65], v[128:129]
	v_pk_add_f32 v[66:67], v[66:67], v[130:131]
	s_waitcnt vmcnt(14)
	v_pk_add_f32 v[68:69], v[68:69], v[132:133]
	v_pk_add_f32 v[70:71], v[70:71], v[134:135]
	s_waitcnt vmcnt(13)
	v_pk_add_f32 v[72:73], v[72:73], v[136:137]
	v_pk_add_f32 v[74:75], v[74:75], v[138:139]
	s_waitcnt vmcnt(12)
	v_pk_add_f32 v[76:77], v[76:77], v[140:141]
	v_pk_add_f32 v[78:79], v[78:79], v[142:143]
	s_waitcnt vmcnt(11)
	v_pk_add_f32 v[80:81], v[80:81], v[144:145]
	v_pk_add_f32 v[82:83], v[82:83], v[146:147]
	s_waitcnt vmcnt(10)
	v_pk_add_f32 v[84:85], v[84:85], v[148:149]
	v_pk_add_f32 v[86:87], v[86:87], v[150:151]
	s_waitcnt vmcnt(9)
	v_pk_add_f32 v[88:89], v[88:89], v[152:153]
	v_pk_add_f32 v[90:91], v[90:91], v[154:155]
	s_waitcnt vmcnt(8)
	v_pk_add_f32 v[92:93], v[92:93], v[156:157]
	v_pk_add_f32 v[94:95], v[94:95], v[158:159]
	s_waitcnt vmcnt(7)
	v_pk_add_f32 v[96:97], v[96:97], v[212:213]
	v_pk_add_f32 v[98:99], v[98:99], v[214:215]
	s_waitcnt vmcnt(6)
	v_pk_add_f32 v[100:101], v[100:101], v[216:217]
	v_pk_add_f32 v[102:103], v[102:103], v[218:219]
	s_waitcnt vmcnt(5)
	v_pk_add_f32 v[104:105], v[104:105], v[220:221]
	v_pk_add_f32 v[106:107], v[106:107], v[222:223]
	s_waitcnt vmcnt(4)
	v_pk_add_f32 v[108:109], v[108:109], v[224:225]
	v_pk_add_f32 v[110:111], v[110:111], v[226:227]
	s_waitcnt vmcnt(3)
	v_pk_add_f32 v[112:113], v[112:113], v[228:229]
	v_pk_add_f32 v[114:115], v[114:115], v[230:231]
	s_waitcnt vmcnt(2)
	v_pk_add_f32 v[116:117], v[116:117], v[232:233]
	v_pk_add_f32 v[118:119], v[118:119], v[234:235]
	s_waitcnt vmcnt(1)
	v_pk_add_f32 v[120:121], v[120:121], v[188:189]
	v_pk_add_f32 v[122:123], v[122:123], v[190:191]
	s_waitcnt vmcnt(0)
	v_pk_add_f32 v[124:125], v[124:125], v[236:237]
	v_pk_add_f32 v[126:127], v[126:127], v[238:239]
	s_branch .Lsk_epi_normal
.Lsk_rd_hi:
	s_add_u32 s84, s82, 0
	s_addc_u32 s85, s83, 0
	global_load_dwordx4 v[128:131], v186, s[84:85]
	global_load_dwordx4 v[132:135], v186, s[84:85] offset:1024
	global_load_dwordx4 v[136:139], v186, s[84:85] offset:2048
	global_load_dwordx4 v[140:143], v186, s[84:85] offset:3072
	s_add_u32 s84, s84, 0x1000
	s_addc_u32 s85, s85, 0
	global_load_dwordx4 v[144:147], v186, s[84:85]
	global_load_dwordx4 v[148:151], v186, s[84:85] offset:1024
	global_load_dwordx4 v[152:155], v186, s[84:85] offset:2048
	global_load_dwordx4 v[156:159], v186, s[84:85] offset:3072
	s_add_u32 s84, s84, 0x1000
	s_addc_u32 s85, s85, 0
	global_load_dwordx4 v[212:215], v186, s[84:85]
	global_load_dwordx4 v[216:219], v186, s[84:85] offset:1024
	global_load_dwordx4 v[220:223], v186, s[84:85] offset:2048
	global_load_dwordx4 v[224:227], v186, s[84:85] offset:3072
	s_add_u32 s84, s84, 0x1000
	s_addc_u32 s85, s85, 0
	global_load_dwordx4 v[228:231], v186, s[84:85]
	global_load_dwordx4 v[232:235], v186, s[84:85] offset:1024
	global_load_dwordx4 v[188:191], v186, s[84:85] offset:2048
	global_load_dwordx4 v[236:239], v186, s[84:85] offset:3072
	s_waitcnt vmcnt(15)
	v_pk_add_f32 v[0:1], v[0:1], v[128:129]
	v_pk_add_f32 v[2:3], v[2:3], v[130:131]
	s_add_u32 s84, s84, 0x3d000
	s_addc_u32 s85, s85, 0
	global_load_dwordx4 v[128:131], v186, s[84:85]
	s_waitcnt vmcnt(15)
	v_pk_add_f32 v[4:5], v[4:5], v[132:133]
	v_pk_add_f32 v[6:7], v[6:7], v[134:135]
	global_load_dwordx4 v[132:135], v186, s[84:85] offset:1024
	s_waitcnt vmcnt(15)
	v_pk_add_f32 v[8:9], v[8:9], v[136:137]
	v_pk_add_f32 v[10:11], v[10:11], v[138:139]
	global_load_dwordx4 v[136:139], v186, s[84:85] offset:2048
	s_waitcnt vmcnt(15)
	v_pk_add_f32 v[12:13], v[12:13], v[140:141]
	v_pk_add_f32 v[14:15], v[14:15], v[142:143]
	global_load_dwordx4 v[140:143], v186, s[84:85] offset:3072
	s_waitcnt vmcnt(15)
	v_pk_add_f32 v[16:17], v[16:17], v[144:145]
	v_pk_add_f32 v[18:19], v[18:19], v[146:147]
	s_add_u32 s84, s84, 0x1000
	s_addc_u32 s85, s85, 0
	global_load_dwordx4 v[144:147], v186, s[84:85]
	s_waitcnt vmcnt(15)
; template <class Epi, class Sched, bool ALIGN_EPI = false, bool SP2 = false>
; __device__ __forceinline__ void gemm_phase(PG8_LAS unsigned char* lds, const Gemm g, const Sched& S, const Epi& E) {
;     ...
;         if constexpr (!Epi::AFTER_DRAIN) { E(acc, cur, wr, wc, fr, fq); S.done(cur); }
;     DI void operator()(const f32x4 (&acc)[2][2][4][2], const Unit& u, int wr, int wc, int fr, int fq) const {
;         asm volatile("" : "+v"(fr), "+v"(fq));
;         const int row0 = u.pm * 256 + wr * 64 + fr, col0 = u.pn * 256 + wc * 32 + 8 * fq;
	v_pk_add_f32 v[20:21], v[20:21], v[148:149]
	v_pk_add_f32 v[22:23], v[22:23], v[150:151]
	global_load_dwordx4 v[148:151], v186, s[84:85] offset:1024
	s_waitcnt vmcnt(15)
	v_pk_add_f32 v[24:25], v[24:25], v[152:153]
	v_pk_add_f32 v[26:27], v[26:27], v[154:155]
	global_load_dwordx4 v[152:155], v186, s[84:85] offset:2048
	s_waitcnt vmcnt(15)
	v_pk_add_f32 v[28:29], v[28:29], v[156:157]
	v_pk_add_f32 v[30:31], v[30:31], v[158:159]
	global_load_dwordx4 v[156:159], v186, s[84:85] offset:3072
	s_waitcnt vmcnt(15)
	v_pk_add_f32 v[32:33], v[32:33], v[212:213]
	v_pk_add_f32 v[34:35], v[34:35], v[214:215]
	s_add_u32 s84, s84, 0x1000
	s_addc_u32 s85, s85, 0
	global_load_dwordx4 v[212:215], v186, s[84:85]
	s_waitcnt vmcnt(15)
	v_pk_add_f32 v[36:37], v[36:37], v[216:217]
	v_pk_add_f32 v[38:39], v[38:39], v[218:219]
	global_load_dwordx4 v[216:219], v186, s[84:85] offset:1024
	s_waitcnt vmcnt(15)
	v_pk_add_f32 v[40:41], v[40:41], v[220:221]
	v_pk_add_f32 v[42:43], v[42:43], v[222:223]
	global_load_dwordx4 v[220:223], v186, s[84:85] offset:2048
	s_waitcnt vmcnt(15)
	v_pk_add_f32 v[44:45], v[44:45], v[224:225]
	v_pk_add_f32 v[46:47], v[46:47], v[226:227]
	global_load_dwordx4 v[224:227], v186, s[84:85] offset:3072
	s_waitcnt vmcnt(15)
	v_pk_add_f32 v[48:49], v[48:49], v[228:229]
	v_pk_add_f32 v[50:51], v[50:51], v[230:231]
	s_add_u32 s84, s84, 0x1000
	s_addc_u32 s85, s85, 0
	global_load_dwordx4 v[228:231], v186, s[84:85]
	s_waitcnt vmcnt(15)
	v_pk_add_f32 v[52:53], v[52:53], v[232:233]
	v_pk_add_f32 v[54:55], v[54:55], v[234:235]
	global_load_dwordx4 v[232:235], v186, s[84:85] offset:1024
	s_waitcnt vmcnt(15)
	v_pk_add_f32 v[56:57], v[56:57], v[188:189]
	v_pk_add_f32 v[58:59], v[58:59], v[190:191]
	global_load_dwordx4 v[188:191], v186, s[84:85] offset:2048
	s_waitcnt vmcnt(15)
	v_pk_add_f32 v[60:61], v[60:61], v[236:237]
	v_pk_add_f32 v[62:63], v[62:63], v[238:239]
	global_load_dwordx4 v[236:239], v186, s[84:85] offset:3072
	s_waitcnt vmcnt(15)
	v_pk_add_f32 v[0:1], v[0:1], v[128:129]
	v_pk_add_f32 v[2:3], v[2:3], v[130:131]
	s_add_u32 s84, s84, 0x3d000
	s_addc_u32 s85, s85, 0
	global_load_dwordx4 v[128:131], v186, s[84:85]
	s_waitcnt vmcnt(15)
	v_pk_add_f32 v[4:5], v[4:5], v[132:133]
	v_pk_add_f32 v[6:7], v[6:7], v[134:135]
	global_load_dwordx4 v[132:135], v186, s[84:85] offset:1024
	s_waitcnt vmcnt(15)
	v_pk_add_f32 v[8:9], v[8:9], v[136:137]
	v_pk_add_f32 v[10:11], v[10:11], v[138:139]
	global_load_dwordx4 v[136:139], v186, s[84:85] offset:2048
	s_waitcnt vmcnt(15)
	v_pk_add_f32 v[12:13], v[12:13], v[140:141]
	v_pk_add_f32 v[14:15], v[14:15], v[142:143]
	global_load_dwordx4 v[140:143], v186, s[84:85] offset:3072
	s_waitcnt vmcnt(15)
	v_pk_add_f32 v[16:17], v[16:17], v[144:145]
	v_pk_add_f32 v[18:19], v[18:19], v[146:147]
	s_add_u32 s84, s84, 0x1000
	s_addc_u32 s85, s85, 0
	global_load_dwordx4 v[144:147], v186, s[84:85]
	s_waitcnt vmcnt(15)
	v_pk_add_f32 v[20:21], v[20:21], v[148:149]
	v_pk_add_f32 v[22:23], v[22:23], v[150:151]
	global_load_dwordx4 v[148:151], v186, s[84:85] offset:1024
	s_waitcnt vmcnt(15)
	v_pk_add_f32 v[24:25], v[24:25], v[152:153]
	v_pk_add_f32 v[26:27], v[26:27], v[154:155]
	global_load_dwordx4 v[152:155], v186, s[84:85] offset:2048
	s_waitcnt vmcnt(15)
	v_pk_add_f32 v[28:29], v[28:29], v[156:157]
	v_pk_add_f32 v[30:31], v[30:31], v[158:159]
	global_load_dwordx4 v[156:159], v186, s[84:85] offset:3072
	s_waitcnt vmcnt(15)
	v_pk_add_f32 v[32:33], v[32:33], v[212:213]
	v_pk_add_f32 v[34:35], v[34:35], v[214:215]
	s_add_u32 s84, s84, 0x1000
	s_addc_u32 s85, s85, 0
	global_load_dwordx4 v[212:215], v186, s[84:85]
	s_waitcnt vmcnt(15)
	v_pk_add_f32 v[36:37], v[36:37], v[216:217]
	v_pk_add_f32 v[38:39], v[38:39], v[218:219]
	global_load_dwordx4 v[216:219], v186, s[84:85] offset:1024
	s_waitcnt vmcnt(15)
	v_pk_add_f32 v[40:41], v[40:41], v[220:221]
	v_pk_add_f32 v[42:43], v[42:43], v[222:223]
	global_load_dwordx4 v[220:223], v186, s[84:85] offset:2048
	s_waitcnt vmcnt(15)
	v_pk_add_f32 v[44:45], v[44:45], v[224:225]
	v_pk_add_f32 v[46:47], v[46:47], v[226:227]
	global_load_dwordx4 v[224:227], v186, s[84:85] offset:3072
	s_waitcnt vmcnt(15)
	v_pk_add_f32 v[48:49], v[48:49], v[228:229]
	v_pk_add_f32 v[50:51], v[50:51], v[230:231]
	s_add_u32 s84, s84, 0x1000
	s_addc_u32 s85, s85, 0
	global_load_dwordx4 v[228:231], v186, s[84:85]
	s_waitcnt vmcnt(15)
	v_pk_add_f32 v[52:53], v[52:53], v[232:233]
	v_pk_add_f32 v[54:55], v[54:55], v[234:235]
	global_load_dwordx4 v[232:235], v186, s[84:85] offset:1024
	s_waitcnt vmcnt(15)
	v_pk_add_f32 v[56:57], v[56:57], v[188:189]
	v_pk_add_f32 v[58:59], v[58:59], v[190:191]
	global_load_dwordx4 v[188:191], v186, s[84:85] offset:2048
	s_waitcnt vmcnt(15)
	v_pk_add_f32 v[60:61], v[60:61], v[236:237]
	v_pk_add_f32 v[62:63], v[62:63], v[238:239]
	global_load_dwordx4 v[236:239], v186, s[84:85] offset:3072
	s_waitcnt vmcnt(15)
	v_pk_add_f32 v[0:1], v[0:1], v[128:129]
	v_pk_add_f32 v[2:3], v[2:3], v[130:131]
	s_waitcnt vmcnt(14)
	v_pk_add_f32 v[4:5], v[4:5], v[132:133]
	v_pk_add_f32 v[6:7], v[6:7], v[134:135]
	s_waitcnt vmcnt(13)
	v_pk_add_f32 v[8:9], v[8:9], v[136:137]
	v_pk_add_f32 v[10:11], v[10:11], v[138:139]
	s_waitcnt vmcnt(12)
	v_pk_add_f32 v[12:13], v[12:13], v[140:141]
	v_pk_add_f32 v[14:15], v[14:15], v[142:143]
	s_waitcnt vmcnt(11)
	v_pk_add_f32 v[16:17], v[16:17], v[144:145]
	v_pk_add_f32 v[18:19], v[18:19], v[146:147]
	s_waitcnt vmcnt(10)
	v_pk_add_f32 v[20:21], v[20:21], v[148:149]
	v_pk_add_f32 v[22:23], v[22:23], v[150:151]
	s_waitcnt vmcnt(9)
	v_pk_add_f32 v[24:25], v[24:25], v[152:153]
	v_pk_add_f32 v[26:27], v[26:27], v[154:155]
	s_waitcnt vmcnt(8)
	v_pk_add_f32 v[28:29], v[28:29], v[156:157]
	v_pk_add_f32 v[30:31], v[30:31], v[158:159]
	s_waitcnt vmcnt(7)
	v_pk_add_f32 v[32:33], v[32:33], v[212:213]
	v_pk_add_f32 v[34:35], v[34:35], v[214:215]
	s_waitcnt vmcnt(6)
	v_pk_add_f32 v[36:37], v[36:37], v[216:217]
	v_pk_add_f32 v[38:39], v[38:39], v[218:219]
	s_waitcnt vmcnt(5)
	v_pk_add_f32 v[40:41], v[40:41], v[220:221]
	v_pk_add_f32 v[42:43], v[42:43], v[222:223]
	s_waitcnt vmcnt(4)
	v_pk_add_f32 v[44:45], v[44:45], v[224:225]
	v_pk_add_f32 v[46:47], v[46:47], v[226:227]
	s_waitcnt vmcnt(3)
	v_pk_add_f32 v[48:49], v[48:49], v[228:229]
	v_pk_add_f32 v[50:51], v[50:51], v[230:231]
	s_waitcnt vmcnt(2)
	v_pk_add_f32 v[52:53], v[52:53], v[232:233]
	v_pk_add_f32 v[54:55], v[54:55], v[234:235]
	s_waitcnt vmcnt(1)
	v_pk_add_f32 v[56:57], v[56:57], v[188:189]
	v_pk_add_f32 v[58:59], v[58:59], v[190:191]
	s_waitcnt vmcnt(0)
	v_pk_add_f32 v[60:61], v[60:61], v[236:237]
	v_pk_add_f32 v[62:63], v[62:63], v[238:239]
	s_lshl_b32 s42, s42, 8
	s_add_i32 s42, s42, s41
	s_lshl_b32 s6, s43, 8
	s_or_b32 s6, s6, s44
	v_lshl_add_u32 v186, v208, 3, s6
	v_readlane_b32 s6, v253, 22
	v_readlane_b32 s7, v253, 23
	v_ashrrev_i32_e32 v187, 31, v186
	v_add_u32_e32 v190, s42, v173
	v_cndmask_b32_e64 v136, 0, 1, s[8:9]
	v_lshl_add_u64 v[188:189], v[186:187], 1, s[6:7]
	v_cmp_ne_u32_e64 s[6:7], 1, v136
	s_branch .LBB0_548

;     DI void operator()(const f32x4 (&acc)[2][2][4][2], const Unit& u, int wr, int wc, int fr, int fq) const {
;     ...
;         for (int ai = 0; ai < 2; ++ai) {
;             const float* mb = mod + (size_t)row_batch(u.pm * 256 + ai * 128 + wr * 64) * NMOD + gofs;
.LBB0_548:
	s_and_b32 s18, s101, 0x10003
	s_cmp_lg_u32 s18, 0x10002
	s_cbranch_scc1 .Lsk_second_half
	s_mov_b64 s[4:5], -1
	s_branch .LBB0_441

; #define LAS __attribute__((address_space(3)))
; DI void p0_prologue(const Args& a, LAS unsigned char* lds, int tid, int wave, int lane, bool first) {
;     ...
;     LAS float* scr = (LAS float*)(lds + wave * 16384);
;     const int gw = blockIdx.x * 8 + wave, NGW = gridDim.x * 8;
;     constexpr int I_UP = (D / 64) * (NUP / 32), I_DN = (FF / 64) * (D / 32), I_IN = (D / 64) * (NIN / 32), I_OUT = (D / 64) * (D / 32);
;     constexpr int NITEMS = 2 * I_UP + 2 * I_DN + I_IN + I_OUT;
;     for (int it = gw; it < NITEMS; it += NGW) {
.LBB0_648:
	v_readlane_b32 s92, v255, 31
	v_readlane_b32 s4, v255, 18
	s_cmpk_lg_i32 s92, 0x100
	s_cbranch_scc1 .Lno_tail
	s_cmp_eq_u32 s77, 3
	s_cbranch_scc1 .Ltail3
	s_cmp_lg_u32 s77, 8
	s_cbranch_scc1 .Lno_tail
	s_cmp_lt_u32 s4, 32
	s_cbranch_scc1 .Lno_tail
	v_readlane_b32 s8, v255, 49
	s_lshl_b32 s4, s4, 3
	s_add_i32 s100, s4, s8
	s_addk_i32 s100, 0xff00
	s_movk_i32 s101, 0x700
	s_branch .Ltail_go
.Ltail3:
	s_cmpk_lt_u32 s4, 0x80
	s_cbranch_scc1 .Lno_tail
	v_readlane_b32 s8, v255, 49
	s_lshl_b32 s4, s4, 3
	s_add_i32 s100, s4, s8
	s_addk_i32 s100, 0xfc00
	s_movk_i32 s101, 0x400
.Ltail_go:
	s_waitcnt vmcnt(0) lgkmcnt(0)
	v_mov_b32_e32 v172, v194
	v_mov_b32_e32 v161, 0
	v_and_b32_e32 v207, 63, v172
	v_readlane_b32 s34, v255, 43
	v_readlane_b32 s38, v255, 21
	v_readlane_b32 s39, v255, 22
	v_readlane_b32 s40, v255, 23
	v_readlane_b32 s41, v255, 24
	v_readlane_b32 s42, v255, 25
	v_readlane_b32 s43, v255, 26
	v_readlane_b32 s90, v255, 29
	v_readlane_b32 s91, v255, 30
	s_mov_b32 s36, 0x800000
	s_mov_b32 s53, 0
	s_movk_i32 s79, 0x84
	s_movk_i32 s73, 0x3800
	s_movk_i32 s76, 0x5800
	s_branch .Ltr_setup

; DI void p0_prologue(const Args& a, LAS unsigned char* lds, int tid, int wave, int lane, bool first) {
;     ...
;     for (int it = gw; it < NITEMS; it += NGW) {
;         int r = it;
;         if (r < 2 * I_UP) { const int which = r >= I_UP; r -= which * I_UP; const int nb = r % (NUP / 32), kb = r / (NUP / 32);
;             p0_transpose_item(a.in[which ? 18 : 12], D, NUP, srccol_up(32 * nb), (bf16_t*)(ws + (which ? WS_WUP2 : WS_WUP1)), 32 * nb, 64 * kb, scr, lane); continue; }
;         r -= 2 * I_UP;
;         if (r < 2 * I_DN) { const int which = r >= I_DN; r -= which * I_DN; const int nb = r % (D / 32), kb = r / (D / 32);
;             p0_transpose_item(a.in[which ? 19 : 13], FF, D, 32 * nb, (bf16_t*)(ws + (which ? WS_WDN2 : WS_WDN1)), 32 * nb, 64 * kb, scr, lane); continue; }
;         r -= 2 * I_DN;
;         if (r < I_IN) { const int nb = r % (NIN / 32), kb = r / (NIN / 32);
;             p0_transpose_item(a.in[14], D, NIN, srccol_in(32 * nb), (bf16_t*)(ws + WS_WIN), 32 * nb, 64 * kb, scr, lane); continue; }
;         r -= I_IN;
;         { const int nb = r % (D / 32), kb = r / (D / 32);
;             p0_transpose_item(a.in[17], D, D, 32 * nb, (bf16_t*)(ws + WS_WOUT), 32 * nb, 64 * kb, scr, lane); }
;     }
.Ltr_map_tail:
	s_cmp_lg_u32 s77, 3
	s_cbranch_scc1 .Ltr_map_tail8
	s_cmpk_gt_i32 s100, 0x8ff
	s_cbranch_scc1 .LBB0_744
	s_add_i32 s10, s100, 0x2100
	s_branch .LBB0_720
.Ltr_map_tail8:
	s_cmpk_gt_i32 s100, 0x107f
	s_cbranch_scc1 .LBB0_744
	s_add_i32 s10, s100, 0xb00
	s_cmpk_lt_i32 s100, 0xb00
	s_cbranch_scc1 .LBB0_720
	s_addk_i32 s10, 0x580
	s_branch .LBB0_720
